# prompt GLA output item: the two 8-byte output stores per lane merged into one 16-byte store
# baseline (speedup 1.0000x reference)
; __device__ __forceinline__ unsigned cvt_pk_bf16(float lo, float hi) { unsigned r; asm("v_cvt_pk_bf16_f32 %0, %1, %2" : "=v"(r) : "v"(lo), "v"(hi)); return r; }
; __device__ __forceinline__ float bflo(unsigned w) { return __uint_as_float(w << 16); }
; __device__ __forceinline__ float bfhi(unsigned w) { return __uint_as_float(w & 0xffff0000u); }
; __device__ __forceinline__ float silu(float x) { return x / (1.f + __expf(-x)); }
; template <bool SMP>
; __device__ __forceinline__ void gla_out_item(const Params& p, int l, int c, int h, LAS unsigned char* lds) {
;     ...
;     __syncthreads();
;     const float* gn = p.gla_norm_g + l * 256 + w * 32 + fq * 4;
;     const f32x4 g0 = *(const f32x4*)gn, g1 = *(const f32x4*)(gn + 16);
; #pragma unroll
;     for (int mt = 0; mt < 4; ++mt) {
;         const int t = mt * 16 + fr;
;         float tot = 0.f;
; #pragma unroll
;         for (int ww = 0; ww < 8; ++ww) tot += red[ww * 64 + t];
;         const float rs = rsqrtf(tot * (1.f / 256.f) + EPS);
; #pragma unroll
;         for (int n = 0; n < 2; ++n) {
;             const f32x4 gg = n ? g1 : g0; const u32x2 ga = gav[mt][n];
;             const float o0 = o[mt][n][0] * rs * gg[0] * silu(bflo(ga.x)), o1 = o[mt][n][1] * rs * gg[1] * silu(bfhi(ga.x));
;             const float o2 = o[mt][n][2] * rs * gg[2] * silu(bflo(ga.y)), o3 = o[mt][n][3] * rs * gg[3] * silu(bfhi(ga.y));
;             u32x2 wv; wv.x = cvt_pk_bf16(o0, o1); wv.y = cvt_pk_bf16(o2, o3);
;             *(u32x2*)((u16*)(ws + WS_OBUF) + (size_t)(tok0 + t) * 2048 + h * 256 + w * 32 + n * 16 + fq * 4) = wv;
;         }
.LBB0_676:
	s_or_b64 exec, exec, s[0:1]
	s_lshl_b32 s0, s2, 8
	s_ashr_i32 s1, s0, 31
	s_lshl_b64 s[0:1], s[0:1], 2
	s_add_u32 s0, s46, s0
	s_addc_u32 s1, s47, s1
	s_waitcnt lgkmcnt(0)
	v_lshl_add_u64 v[6:7], v[86:87], 2, s[0:1]
	v_lshlrev_b32_e32 v0, 3, v56
	v_lshl_add_u64 v[6:7], v[6:7], 0, v[0:1]
	s_barrier
	global_load_dwordx4 v[14:17], v[6:7], off offset:16
	s_nop 0
	global_load_dwordx4 v[6:9], v[6:7], off
	s_lshl_b32 s0, s6, 1
	v_readlane_b32 s1, v252, 25
	s_add_u32 s0, s1, s0
	v_readlane_b32 s1, v252, 26
	s_addc_u32 s1, s1, 0
	v_lshlrev_b32_e32 v0, 2, v56
	v_lshl_add_u64 v[42:43], v[86:87], 1, s[0:1]
	v_lshl_add_u64 v[42:43], v[42:43], 0, v[0:1]
	v_lshl_add_u32 v0, v90, 2, 0
	v_add_u32_e32 v86, 0x800, v0
	ds_read2_b32 v[44:45], v86 offset1:16
	ds_read2_b32 v[46:47], v86 offset0:64 offset1:80
	ds_read2_b32 v[48:49], v86 offset0:128 offset1:144
	ds_read2_b32 v[50:51], v86 offset0:192 offset1:208
	v_add_u32_e32 v0, 0xc00, v0
	ds_read2_b32 v[52:53], v0 offset1:16
	s_waitcnt lgkmcnt(4)
	v_add_f32_e32 v44, 0, v44
	ds_read2_b32 v[54:55], v0 offset0:64 offset1:80
	s_waitcnt lgkmcnt(4)
	v_add_f32_e32 v44, v44, v46
	ds_read2_b32 v[56:57], v0 offset0:128 offset1:144
	s_waitcnt lgkmcnt(4)
	v_add_f32_e32 v44, v44, v48
	ds_read2_b32 v[58:59], v0 offset0:192 offset1:208
	s_waitcnt lgkmcnt(4)
	v_add_f32_e32 v44, v44, v50
	s_waitcnt lgkmcnt(3)
	v_add_f32_e32 v44, v44, v52
	s_waitcnt lgkmcnt(2)
	v_add_f32_e32 v44, v44, v54
	s_waitcnt lgkmcnt(1)
	v_add_f32_e32 v44, v44, v56
	s_waitcnt lgkmcnt(0)
	v_add_f32_e32 v44, v44, v58
	v_fmamk_f32 v44, v44, 0x3b800000, v203
	v_cmp_gt_f32_e32 vcc, s89, v44
	v_mul_f32_e32 v46, 0x4b800000, v44
	v_lshlrev_b64 v[60:61], 12, v[84:85]
	v_cndmask_b32_e32 v44, v44, v46, vcc
	v_rsq_f32_e32 v44, v44
	v_lshl_add_u64 v[60:61], v[42:43], 0, v[60:61]
	v_mul_f32_e32 v46, 0x45800000, v44
	v_cndmask_b32_e32 v44, v44, v46, vcc
	s_waitcnt vmcnt(5)
	v_lshlrev_b32_e32 v46, 16, v82
	v_mul_f32_e32 v48, 0xbfb8aa3b, v46
	v_exp_f32_e32 v48, v48
	v_mul_f32_e32 v38, v38, v44
	v_mul_f32_e32 v39, v39, v44
	v_mul_f32_e32 v40, v40, v44
	v_add_f32_e32 v48, 1.0, v48
	v_div_scale_f32 v50, s[0:1], v48, v48, v46
	v_rcp_f32_e32 v52, v50
	v_mul_f32_e32 v41, v41, v44
	v_mul_f32_e32 v34, v34, v44
	v_mul_f32_e32 v35, v35, v44
	v_fma_f32 v54, -v50, v52, 1.0
	v_fmac_f32_e32 v52, v54, v52
	v_div_scale_f32 v54, vcc, v46, v48, v46
	v_mul_f32_e32 v56, v54, v52
	v_fma_f32 v58, -v50, v56, v54
	v_fmac_f32_e32 v56, v58, v52
	v_fma_f32 v50, -v50, v56, v54
	v_div_fmas_f32 v50, v50, v52, v56
	v_div_fixup_f32 v46, v50, v48, v46
	v_mul_f32_e32 v36, v36, v44
	v_mul_f32_e32 v37, v37, v44
	s_waitcnt vmcnt(1)
	v_mul_f32_e32 v38, v14, v38
	v_mul_f32_e32 v38, v46, v38
	v_and_b32_e32 v46, 0xffff0000, v82
	v_mul_f32_e32 v48, 0xbfb8aa3b, v46
	v_exp_f32_e32 v48, v48
	v_mul_f32_e32 v39, v15, v39
	v_mul_f32_e32 v40, v16, v40
	v_mul_f32_e32 v41, v17, v41
	v_add_f32_e32 v48, 1.0, v48
	v_div_scale_f32 v50, s[0:1], v48, v48, v46
	v_rcp_f32_e32 v52, v50
	s_waitcnt vmcnt(0)
	v_mul_f32_e32 v34, v6, v34
	v_mul_f32_e32 v35, v7, v35
	v_mul_f32_e32 v36, v8, v36
	v_fma_f32 v54, -v50, v52, 1.0
	v_fmac_f32_e32 v52, v54, v52
	v_div_scale_f32 v54, vcc, v46, v48, v46
	v_mul_f32_e32 v56, v54, v52
	v_fma_f32 v58, -v50, v56, v54
	v_fmac_f32_e32 v56, v58, v52
	v_fma_f32 v50, -v50, v56, v54
	v_div_fmas_f32 v50, v50, v52, v56
	v_div_fixup_f32 v46, v50, v48, v46
	v_mul_f32_e32 v39, v46, v39
	v_lshlrev_b32_e32 v46, 16, v83
	v_mul_f32_e32 v48, 0xbfb8aa3b, v46
	v_exp_f32_e32 v48, v48
	v_cvt_pk_bf16_f32 v38, v38, v39
	v_mul_f32_e32 v37, v9, v37
	v_add_f32_e32 v48, 1.0, v48
	v_div_scale_f32 v50, s[0:1], v48, v48, v46
	v_rcp_f32_e32 v52, v50
	s_nop 0
	v_fma_f32 v54, -v50, v52, 1.0
	v_fmac_f32_e32 v52, v54, v52
	v_div_scale_f32 v54, vcc, v46, v48, v46
	v_mul_f32_e32 v56, v54, v52
	v_fma_f32 v58, -v50, v56, v54
	v_fmac_f32_e32 v56, v58, v52
	v_fma_f32 v50, -v50, v56, v54
	v_div_fmas_f32 v50, v50, v52, v56
	v_div_fixup_f32 v46, v50, v48, v46
	v_mul_f32_e32 v40, v46, v40
	v_and_b32_e32 v46, 0xffff0000, v83
	v_mul_f32_e32 v48, 0xbfb8aa3b, v46
	v_exp_f32_e32 v48, v48
	s_nop 0
	v_add_f32_e32 v48, 1.0, v48
	v_div_scale_f32 v50, s[0:1], v48, v48, v46
	v_rcp_f32_e32 v52, v50
	s_nop 0
	v_fma_f32 v54, -v50, v52, 1.0
	v_fmac_f32_e32 v52, v54, v52
	v_div_scale_f32 v54, vcc, v46, v48, v46
	v_mul_f32_e32 v56, v54, v52
	v_fma_f32 v58, -v50, v56, v54
	v_fmac_f32_e32 v56, v58, v52
	v_fma_f32 v50, -v50, v56, v54
	v_div_fmas_f32 v50, v50, v52, v56
	v_div_fixup_f32 v46, v50, v48, v46
	v_mul_f32_e32 v41, v46, v41
	v_cvt_pk_bf16_f32 v39, v40, v41
	v_mov_b32_e32 v118, v38
	v_mov_b32_e32 v119, v39
	v_lshlrev_b32_e32 v38, 16, v80
	v_mul_f32_e32 v39, 0xbfb8aa3b, v38
	v_exp_f32_e32 v39, v39
	s_nop 0
	v_add_f32_e32 v39, 1.0, v39
	v_div_scale_f32 v40, s[0:1], v39, v39, v38
	v_rcp_f32_e32 v41, v40
	s_nop 0
	v_fma_f32 v46, -v40, v41, 1.0
	v_fmac_f32_e32 v41, v46, v41
	v_div_scale_f32 v46, vcc, v38, v39, v38
	v_mul_f32_e32 v48, v46, v41
	v_fma_f32 v50, -v40, v48, v46
	v_fmac_f32_e32 v48, v50, v41
	v_fma_f32 v40, -v40, v48, v46
	v_div_fmas_f32 v40, v40, v41, v48
	v_div_fixup_f32 v38, v40, v39, v38
	v_mul_f32_e32 v34, v38, v34
	v_and_b32_e32 v38, 0xffff0000, v80
	v_mul_f32_e32 v39, 0xbfb8aa3b, v38
	v_exp_f32_e32 v39, v39
	s_nop 0
	v_add_f32_e32 v39, 1.0, v39
	v_div_scale_f32 v40, s[0:1], v39, v39, v38
	v_rcp_f32_e32 v41, v40
	s_nop 0
	v_fma_f32 v46, -v40, v41, 1.0
	v_fmac_f32_e32 v41, v46, v41
	v_div_scale_f32 v46, vcc, v38, v39, v38
	v_mul_f32_e32 v48, v46, v41
	v_fma_f32 v50, -v40, v48, v46
	v_fmac_f32_e32 v48, v50, v41
	v_fma_f32 v40, -v40, v48, v46
	v_div_fmas_f32 v40, v40, v41, v48
	v_div_fixup_f32 v38, v40, v39, v38
	v_mul_f32_e32 v35, v38, v35
; __device__ __forceinline__ unsigned cvt_pk_bf16(float lo, float hi) { unsigned r; asm("v_cvt_pk_bf16_f32 %0, %1, %2" : "=v"(r) : "v"(lo), "v"(hi)); return r; }
; __device__ __forceinline__ float bflo(unsigned w) { return __uint_as_float(w << 16); }
; __device__ __forceinline__ float bfhi(unsigned w) { return __uint_as_float(w & 0xffff0000u); }
; __device__ __forceinline__ float silu(float x) { return x / (1.f + __expf(-x)); }
; template <bool SMP>
; __device__ __forceinline__ void gla_out_item(const Params& p, int l, int c, int h, LAS unsigned char* lds) {
;     ...
;     for (int mt = 0; mt < 4; ++mt) {
;         const int t = mt * 16 + fr;
;         float tot = 0.f;
; #pragma unroll
;         for (int ww = 0; ww < 8; ++ww) tot += red[ww * 64 + t];
;         const float rs = rsqrtf(tot * (1.f / 256.f) + EPS);
; #pragma unroll
;         for (int n = 0; n < 2; ++n) {
;             const f32x4 gg = n ? g1 : g0; const u32x2 ga = gav[mt][n];
;             const float o0 = o[mt][n][0] * rs * gg[0] * silu(bflo(ga.x)), o1 = o[mt][n][1] * rs * gg[1] * silu(bfhi(ga.x));
;             const float o2 = o[mt][n][2] * rs * gg[2] * silu(bflo(ga.y)), o3 = o[mt][n][3] * rs * gg[3] * silu(bfhi(ga.y));
;             u32x2 wv; wv.x = cvt_pk_bf16(o0, o1); wv.y = cvt_pk_bf16(o2, o3);
;             *(u32x2*)((u16*)(ws + WS_OBUF) + (size_t)(tok0 + t) * 2048 + h * 256 + w * 32 + n * 16 + fq * 4) = wv;
;         }
	v_lshlrev_b32_e32 v38, 16, v81
	v_mul_f32_e32 v39, 0xbfb8aa3b, v38
	v_exp_f32_e32 v39, v39
	v_cvt_pk_bf16_f32 v34, v34, v35
	s_nop 0
	v_add_f32_e32 v39, 1.0, v39
	v_div_scale_f32 v40, s[0:1], v39, v39, v38
	v_rcp_f32_e32 v41, v40
	s_nop 0
	v_fma_f32 v46, -v40, v41, 1.0
	v_fmac_f32_e32 v41, v46, v41
	v_div_scale_f32 v46, vcc, v38, v39, v38
	v_mul_f32_e32 v48, v46, v41
	v_fma_f32 v50, -v40, v48, v46
	v_fmac_f32_e32 v48, v50, v41
	v_fma_f32 v40, -v40, v48, v46
	v_div_fmas_f32 v40, v40, v41, v48
	v_div_fixup_f32 v38, v40, v39, v38
	v_mul_f32_e32 v36, v38, v36
	v_and_b32_e32 v38, 0xffff0000, v81
	v_mul_f32_e32 v39, 0xbfb8aa3b, v38
	v_exp_f32_e32 v39, v39
	s_nop 0
	v_add_f32_e32 v39, 1.0, v39
	v_div_scale_f32 v40, s[0:1], v39, v39, v38
	v_rcp_f32_e32 v41, v40
	s_nop 0
	v_fma_f32 v44, -v40, v41, 1.0
	v_fmac_f32_e32 v41, v44, v41
	v_div_scale_f32 v44, vcc, v38, v39, v38
	v_mul_f32_e32 v46, v44, v41
	v_fma_f32 v48, -v40, v46, v44
	v_fmac_f32_e32 v46, v48, v41
	v_fma_f32 v40, -v40, v46, v44
	v_div_fmas_f32 v40, v40, v41, v46
	v_div_fixup_f32 v38, v40, v39, v38
	v_mul_f32_e32 v37, v38, v37
	v_cvt_pk_bf16_f32 v35, v36, v37
	v_mov_b32_e32 v116, v34
	v_mov_b32_e32 v117, v35
	global_store_dwordx4 v[60:61], v[116:119], off
	v_add_f32_e32 v34, 0, v45
	v_add_f32_e32 v34, v34, v47
	v_add_f32_e32 v34, v34, v49
	v_add_f32_e32 v34, v34, v51
	v_lshlrev_b32_e32 v37, 16, v76
	v_add_f32_e32 v34, v34, v53
	v_mul_f32_e32 v38, 0xbfb8aa3b, v37
	v_add_f32_e32 v34, v34, v55
	v_exp_f32_e32 v38, v38
	v_add_f32_e32 v34, v34, v57
	v_add_f32_e32 v34, v34, v59
	v_fmamk_f32 v34, v34, 0x3b800000, v203
	v_cmp_gt_f32_e32 vcc, s89, v34
	v_mul_f32_e32 v35, 0x4b800000, v34
	v_add_f32_e32 v38, 1.0, v38
	v_cndmask_b32_e32 v34, v34, v35, vcc
	v_div_scale_f32 v39, s[0:1], v38, v38, v37
	v_rsq_f32_e32 v34, v34
	v_rcp_f32_e32 v40, v39
	v_mul_f32_e32 v35, 0x45800000, v34
	v_fma_f32 v41, -v39, v40, 1.0
	v_cndmask_b32_e32 v36, v34, v35, vcc
	v_fmac_f32_e32 v40, v41, v40
	v_div_scale_f32 v41, vcc, v37, v38, v37
	v_mul_f32_e32 v44, v41, v40
	v_fma_f32 v45, -v39, v44, v41
	v_fmac_f32_e32 v44, v45, v40
	v_fma_f32 v39, -v39, v44, v41
	v_mul_f32_e32 v30, v30, v36
	v_div_fmas_f32 v39, v39, v40, v44
	v_mul_f32_e32 v30, v14, v30
	v_div_fixup_f32 v37, v39, v38, v37
	v_mul_f32_e32 v30, v37, v30
	v_and_b32_e32 v37, 0xffff0000, v76
	v_mul_f32_e32 v38, 0xbfb8aa3b, v37
	v_exp_f32_e32 v38, v38
	v_mul_f32_e32 v31, v31, v36
	v_mul_f32_e32 v31, v15, v31
	v_mul_f32_e32 v32, v32, v36
	v_add_f32_e32 v38, 1.0, v38
	v_div_scale_f32 v39, s[0:1], v38, v38, v37
	v_rcp_f32_e32 v40, v39
	v_mul_f32_e32 v32, v16, v32
	v_lshlrev_b64 v[34:35], 12, v[78:79]
	v_mul_f32_e32 v33, v33, v36
	v_fma_f32 v41, -v39, v40, 1.0
	v_fmac_f32_e32 v40, v41, v40
	v_div_scale_f32 v41, vcc, v37, v38, v37
	v_mul_f32_e32 v44, v41, v40
	v_fma_f32 v45, -v39, v44, v41
	v_fmac_f32_e32 v44, v45, v40
	v_fma_f32 v39, -v39, v44, v41
	v_div_fmas_f32 v39, v39, v40, v44
	v_div_fixup_f32 v37, v39, v38, v37
	v_mul_f32_e32 v31, v37, v31
	v_lshlrev_b32_e32 v37, 16, v77
	v_mul_f32_e32 v38, 0xbfb8aa3b, v37
	v_exp_f32_e32 v38, v38
	v_lshl_add_u64 v[34:35], v[42:43], 0, v[34:35]
	v_mul_f32_e32 v33, v17, v33
	v_cvt_pk_bf16_f32 v30, v30, v31
	v_add_f32_e32 v38, 1.0, v38
	v_div_scale_f32 v39, s[0:1], v38, v38, v37
	v_rcp_f32_e32 v40, v39
	v_mul_f32_e32 v26, v26, v36
	v_mul_f32_e32 v26, v6, v26
	v_mul_f32_e32 v27, v27, v36
	v_fma_f32 v41, -v39, v40, 1.0
	v_fmac_f32_e32 v40, v41, v40
	v_div_scale_f32 v41, vcc, v37, v38, v37
	v_mul_f32_e32 v44, v41, v40
	v_fma_f32 v45, -v39, v44, v41
	v_fmac_f32_e32 v44, v45, v40
	v_fma_f32 v39, -v39, v44, v41
	v_div_fmas_f32 v39, v39, v40, v44
	v_div_fixup_f32 v37, v39, v38, v37
	v_mul_f32_e32 v32, v37, v32
	v_and_b32_e32 v37, 0xffff0000, v77
	v_mul_f32_e32 v38, 0xbfb8aa3b, v37
	v_exp_f32_e32 v38, v38
	v_mul_f32_e32 v27, v7, v27
	v_mul_f32_e32 v28, v28, v36
	v_mul_f32_e32 v28, v8, v28
	v_add_f32_e32 v38, 1.0, v38
	v_div_scale_f32 v39, s[0:1], v38, v38, v37
	v_rcp_f32_e32 v40, v39
	v_mul_f32_e32 v29, v29, v36
	v_mul_f32_e32 v29, v9, v29
	v_fma_f32 v41, -v39, v40, 1.0
	v_fmac_f32_e32 v40, v41, v40
	v_div_scale_f32 v41, vcc, v37, v38, v37
	v_mul_f32_e32 v44, v41, v40
	v_fma_f32 v45, -v39, v44, v41
	v_fmac_f32_e32 v44, v45, v40
	v_fma_f32 v39, -v39, v44, v41
	v_div_fmas_f32 v39, v39, v40, v44
	v_div_fixup_f32 v37, v39, v38, v37
	v_mul_f32_e32 v33, v37, v33
	v_cvt_pk_bf16_f32 v31, v32, v33
	v_mov_b32_e32 v118, v30
	v_mov_b32_e32 v119, v31
	v_lshlrev_b32_e32 v30, 16, v74
	v_mul_f32_e32 v31, 0xbfb8aa3b, v30
	v_exp_f32_e32 v31, v31
	ds_read2_b32 v[40:41], v0 offset0:224 offset1:240
	v_lshlrev_b64 v[44:45], 12, v[72:73]
	v_lshl_add_u64 v[44:45], v[42:43], 0, v[44:45]
	v_add_f32_e32 v31, 1.0, v31
	v_div_scale_f32 v32, s[0:1], v31, v31, v30
	v_rcp_f32_e32 v33, v32
	s_nop 0
	v_fma_f32 v37, -v32, v33, 1.0
	v_fmac_f32_e32 v33, v37, v33
	v_div_scale_f32 v37, vcc, v30, v31, v30
	v_mul_f32_e32 v38, v37, v33
	v_fma_f32 v39, -v32, v38, v37
	v_fmac_f32_e32 v38, v39, v33
	v_fma_f32 v32, -v32, v38, v37
	v_div_fmas_f32 v32, v32, v33, v38
	v_div_fixup_f32 v30, v32, v31, v30
	v_mul_f32_e32 v26, v30, v26
	v_and_b32_e32 v30, 0xffff0000, v74
	v_mul_f32_e32 v31, 0xbfb8aa3b, v30
	v_exp_f32_e32 v31, v31
	s_nop 0
	v_add_f32_e32 v31, 1.0, v31
	v_div_scale_f32 v32, s[0:1], v31, v31, v30
	v_rcp_f32_e32 v33, v32
	s_nop 0
	v_fma_f32 v37, -v32, v33, 1.0
	v_fmac_f32_e32 v33, v37, v33
	v_div_scale_f32 v37, vcc, v30, v31, v30
	v_mul_f32_e32 v38, v37, v33
	v_fma_f32 v39, -v32, v38, v37
	v_fmac_f32_e32 v38, v39, v33
	v_fma_f32 v32, -v32, v38, v37
	v_div_fmas_f32 v32, v32, v33, v38
	v_div_fixup_f32 v30, v32, v31, v30
	v_mul_f32_e32 v27, v30, v27
	v_lshlrev_b32_e32 v30, 16, v75
; __device__ __forceinline__ unsigned cvt_pk_bf16(float lo, float hi) { unsigned r; asm("v_cvt_pk_bf16_f32 %0, %1, %2" : "=v"(r) : "v"(lo), "v"(hi)); return r; }
; __device__ __forceinline__ float bflo(unsigned w) { return __uint_as_float(w << 16); }
; __device__ __forceinline__ float bfhi(unsigned w) { return __uint_as_float(w & 0xffff0000u); }
; __device__ __forceinline__ float silu(float x) { return x / (1.f + __expf(-x)); }
; template <bool SMP>
; __device__ __forceinline__ void gla_out_item(const Params& p, int l, int c, int h, LAS unsigned char* lds) {
;     ...
;     for (int mt = 0; mt < 4; ++mt) {
;         const int t = mt * 16 + fr;
;         float tot = 0.f;
; #pragma unroll
;         for (int ww = 0; ww < 8; ++ww) tot += red[ww * 64 + t];
;         const float rs = rsqrtf(tot * (1.f / 256.f) + EPS);
; #pragma unroll
;         for (int n = 0; n < 2; ++n) {
;             const f32x4 gg = n ? g1 : g0; const u32x2 ga = gav[mt][n];
;             const float o0 = o[mt][n][0] * rs * gg[0] * silu(bflo(ga.x)), o1 = o[mt][n][1] * rs * gg[1] * silu(bfhi(ga.x));
;             const float o2 = o[mt][n][2] * rs * gg[2] * silu(bflo(ga.y)), o3 = o[mt][n][3] * rs * gg[3] * silu(bfhi(ga.y));
;             u32x2 wv; wv.x = cvt_pk_bf16(o0, o1); wv.y = cvt_pk_bf16(o2, o3);
;             *(u32x2*)((u16*)(ws + WS_OBUF) + (size_t)(tok0 + t) * 2048 + h * 256 + w * 32 + n * 16 + fq * 4) = wv;
;         }
	v_mul_f32_e32 v31, 0xbfb8aa3b, v30
	v_exp_f32_e32 v31, v31
	v_cvt_pk_bf16_f32 v26, v26, v27
	s_nop 0
	v_add_f32_e32 v31, 1.0, v31
	v_div_scale_f32 v32, s[0:1], v31, v31, v30
	v_rcp_f32_e32 v33, v32
	s_nop 0
	v_fma_f32 v37, -v32, v33, 1.0
	v_fmac_f32_e32 v33, v37, v33
	v_div_scale_f32 v37, vcc, v30, v31, v30
	v_mul_f32_e32 v38, v37, v33
	v_fma_f32 v39, -v32, v38, v37
	v_fmac_f32_e32 v38, v39, v33
	v_fma_f32 v32, -v32, v38, v37
	v_div_fmas_f32 v32, v32, v33, v38
	v_div_fixup_f32 v30, v32, v31, v30
	v_mul_f32_e32 v28, v30, v28
	v_and_b32_e32 v30, 0xffff0000, v75
	v_mul_f32_e32 v31, 0xbfb8aa3b, v30
	v_exp_f32_e32 v31, v31
	s_nop 0
	v_add_f32_e32 v31, 1.0, v31
	v_div_scale_f32 v32, s[0:1], v31, v31, v30
	v_rcp_f32_e32 v33, v32
	s_nop 0
	v_fma_f32 v36, -v32, v33, 1.0
	v_fmac_f32_e32 v33, v36, v33
	v_div_scale_f32 v36, vcc, v30, v31, v30
	v_mul_f32_e32 v37, v36, v33
	v_fma_f32 v38, -v32, v37, v36
	v_fmac_f32_e32 v37, v38, v33
	v_fma_f32 v32, -v32, v37, v36
	v_div_fmas_f32 v32, v32, v33, v37
	v_div_fixup_f32 v30, v32, v31, v30
	v_mul_f32_e32 v29, v30, v29
	v_cvt_pk_bf16_f32 v27, v28, v29
	v_mov_b32_e32 v116, v26
	v_mov_b32_e32 v117, v27
	global_store_dwordx4 v[34:35], v[116:119], off
	ds_read2_b32 v[26:27], v86 offset0:32 offset1:48
	ds_read2_b32 v[28:29], v86 offset0:96 offset1:112
	ds_read2_b32 v[30:31], v86 offset0:160 offset1:176
	ds_read2_b32 v[32:33], v86 offset0:224 offset1:240
	ds_read2_b32 v[34:35], v0 offset0:32 offset1:48
	s_waitcnt lgkmcnt(4)
	v_add_f32_e32 v26, 0, v26
	ds_read2_b32 v[36:37], v0 offset0:96 offset1:112
	s_waitcnt lgkmcnt(4)
	v_add_f32_e32 v26, v26, v28
	ds_read2_b32 v[38:39], v0 offset0:160 offset1:176
	s_waitcnt lgkmcnt(4)
	v_add_f32_e32 v26, v26, v30
	s_waitcnt lgkmcnt(3)
	v_add_f32_e32 v26, v26, v32
	s_waitcnt lgkmcnt(2)
	v_add_f32_e32 v26, v26, v34
	s_waitcnt lgkmcnt(1)
	v_add_f32_e32 v26, v26, v36
	s_waitcnt lgkmcnt(0)
	v_add_f32_e32 v26, v26, v38
	v_add_f32_e32 v0, v26, v40
	v_fmamk_f32 v0, v0, 0x3b800000, v203
	v_cmp_gt_f32_e32 vcc, s89, v0
	v_mul_f32_e32 v26, 0x4b800000, v0
	s_nop 0
	v_cndmask_b32_e32 v0, v0, v26, vcc
	v_rsq_f32_e32 v0, v0
	s_nop 0
	v_mul_f32_e32 v26, 0x45800000, v0
	v_cndmask_b32_e32 v0, v0, v26, vcc
	v_lshlrev_b32_e32 v26, 16, v70
	v_mul_f32_e32 v28, 0xbfb8aa3b, v26
	v_exp_f32_e32 v28, v28
	v_mul_f32_e32 v22, v22, v0
	v_mul_f32_e32 v22, v14, v22
	v_mul_f32_e32 v23, v23, v0
	v_add_f32_e32 v28, 1.0, v28
	v_div_scale_f32 v30, s[0:1], v28, v28, v26
	v_rcp_f32_e32 v32, v30
	v_mul_f32_e32 v23, v15, v23
	v_mul_f32_e32 v24, v24, v0
	v_mul_f32_e32 v24, v16, v24
	v_fma_f32 v34, -v30, v32, 1.0
	v_fmac_f32_e32 v32, v34, v32
	v_div_scale_f32 v34, vcc, v26, v28, v26
	v_mul_f32_e32 v36, v34, v32
	v_fma_f32 v38, -v30, v36, v34
	v_fmac_f32_e32 v36, v38, v32
	v_fma_f32 v30, -v30, v36, v34
	v_div_fmas_f32 v30, v30, v32, v36
	v_div_fixup_f32 v26, v30, v28, v26
	v_mul_f32_e32 v22, v26, v22
	v_and_b32_e32 v26, 0xffff0000, v70
	v_mul_f32_e32 v28, 0xbfb8aa3b, v26
	v_exp_f32_e32 v28, v28
	v_mul_f32_e32 v25, v25, v0
	v_mul_f32_e32 v25, v17, v25
	v_mul_f32_e32 v18, v18, v0
	v_add_f32_e32 v28, 1.0, v28
	v_div_scale_f32 v30, s[0:1], v28, v28, v26
	v_rcp_f32_e32 v32, v30
	v_mul_f32_e32 v18, v6, v18
	v_mul_f32_e32 v19, v19, v0
	v_mul_f32_e32 v19, v7, v19
	v_fma_f32 v34, -v30, v32, 1.0
	v_fmac_f32_e32 v32, v34, v32
	v_div_scale_f32 v34, vcc, v26, v28, v26
	v_mul_f32_e32 v36, v34, v32
	v_fma_f32 v38, -v30, v36, v34
	v_fmac_f32_e32 v36, v38, v32
	v_fma_f32 v30, -v30, v36, v34
	v_div_fmas_f32 v30, v30, v32, v36
	v_div_fixup_f32 v26, v30, v28, v26
	v_mul_f32_e32 v23, v26, v23
	v_lshlrev_b32_e32 v26, 16, v71
	v_mul_f32_e32 v28, 0xbfb8aa3b, v26
	v_exp_f32_e32 v28, v28
	v_cvt_pk_bf16_f32 v22, v22, v23
	v_mul_f32_e32 v20, v20, v0
	v_mul_f32_e32 v20, v8, v20
	v_add_f32_e32 v28, 1.0, v28
	v_div_scale_f32 v30, s[0:1], v28, v28, v26
	v_rcp_f32_e32 v32, v30
	v_mul_f32_e32 v0, v21, v0
	v_and_b32_e32 v21, 0xffff0000, v69
	v_mul_f32_e32 v0, v9, v0
	v_fma_f32 v34, -v30, v32, 1.0
	v_fmac_f32_e32 v32, v34, v32
	v_div_scale_f32 v34, vcc, v26, v28, v26
	v_mul_f32_e32 v36, v34, v32
	v_fma_f32 v38, -v30, v36, v34
	v_fmac_f32_e32 v36, v38, v32
	v_fma_f32 v30, -v30, v36, v34
	v_div_fmas_f32 v30, v30, v32, v36
	v_div_fixup_f32 v26, v30, v28, v26
	v_mul_f32_e32 v24, v26, v24
	v_and_b32_e32 v26, 0xffff0000, v71
	v_mul_f32_e32 v28, 0xbfb8aa3b, v26
	v_exp_f32_e32 v28, v28
	s_nop 0
	v_add_f32_e32 v28, 1.0, v28
	v_div_scale_f32 v30, s[0:1], v28, v28, v26
	v_rcp_f32_e32 v32, v30
	s_nop 0
	v_fma_f32 v34, -v30, v32, 1.0
	v_fmac_f32_e32 v32, v34, v32
	v_div_scale_f32 v34, vcc, v26, v28, v26
	v_mul_f32_e32 v36, v34, v32
	v_fma_f32 v38, -v30, v36, v34
	v_fmac_f32_e32 v36, v38, v32
	v_fma_f32 v30, -v30, v36, v34
	v_div_fmas_f32 v30, v30, v32, v36
	v_div_fixup_f32 v26, v30, v28, v26
	v_mul_f32_e32 v25, v26, v25
	v_cvt_pk_bf16_f32 v23, v24, v25
	v_mov_b32_e32 v118, v22
	v_mov_b32_e32 v119, v23
	v_lshlrev_b32_e32 v22, 16, v68
	v_mul_f32_e32 v23, 0xbfb8aa3b, v22
	v_exp_f32_e32 v23, v23
	s_nop 0
	v_add_f32_e32 v23, 1.0, v23
	v_div_scale_f32 v24, s[0:1], v23, v23, v22
	v_rcp_f32_e32 v25, v24
	s_nop 0
	v_fma_f32 v26, -v24, v25, 1.0
	v_fmac_f32_e32 v25, v26, v25
	v_div_scale_f32 v26, vcc, v22, v23, v22
	v_mul_f32_e32 v28, v26, v25
	v_fma_f32 v30, -v24, v28, v26
	v_fmac_f32_e32 v28, v30, v25
	v_fma_f32 v24, -v24, v28, v26
	v_div_fmas_f32 v24, v24, v25, v28
	v_div_fixup_f32 v22, v24, v23, v22
	v_mul_f32_e32 v18, v22, v18
	v_and_b32_e32 v22, 0xffff0000, v68
	v_mul_f32_e32 v23, 0xbfb8aa3b, v22
	v_exp_f32_e32 v23, v23
	s_nop 0
	v_add_f32_e32 v23, 1.0, v23
	v_div_scale_f32 v24, s[0:1], v23, v23, v22
	v_rcp_f32_e32 v25, v24
	s_nop 0
	v_fma_f32 v26, -v24, v25, 1.0
; __device__ __forceinline__ unsigned cvt_pk_bf16(float lo, float hi) { unsigned r; asm("v_cvt_pk_bf16_f32 %0, %1, %2" : "=v"(r) : "v"(lo), "v"(hi)); return r; }
; __device__ __forceinline__ float bflo(unsigned w) { return __uint_as_float(w << 16); }
; __device__ __forceinline__ float bfhi(unsigned w) { return __uint_as_float(w & 0xffff0000u); }
; __device__ __forceinline__ float silu(float x) { return x / (1.f + __expf(-x)); }
; template <bool SMP>
; __device__ __forceinline__ void gla_out_item(const Params& p, int l, int c, int h, LAS unsigned char* lds) {
;     ...
;     for (int mt = 0; mt < 4; ++mt) {
;         const int t = mt * 16 + fr;
;         float tot = 0.f;
; #pragma unroll
;         for (int ww = 0; ww < 8; ++ww) tot += red[ww * 64 + t];
;         const float rs = rsqrtf(tot * (1.f / 256.f) + EPS);
; #pragma unroll
;         for (int n = 0; n < 2; ++n) {
;             const f32x4 gg = n ? g1 : g0; const u32x2 ga = gav[mt][n];
;             const float o0 = o[mt][n][0] * rs * gg[0] * silu(bflo(ga.x)), o1 = o[mt][n][1] * rs * gg[1] * silu(bfhi(ga.x));
;             const float o2 = o[mt][n][2] * rs * gg[2] * silu(bflo(ga.y)), o3 = o[mt][n][3] * rs * gg[3] * silu(bfhi(ga.y));
;             u32x2 wv; wv.x = cvt_pk_bf16(o0, o1); wv.y = cvt_pk_bf16(o2, o3);
;             *(u32x2*)((u16*)(ws + WS_OBUF) + (size_t)(tok0 + t) * 2048 + h * 256 + w * 32 + n * 16 + fq * 4) = wv;
;         }
	v_fmac_f32_e32 v25, v26, v25
	v_div_scale_f32 v26, vcc, v22, v23, v22
	v_mul_f32_e32 v28, v26, v25
	v_fma_f32 v30, -v24, v28, v26
	v_fmac_f32_e32 v28, v30, v25
	v_fma_f32 v24, -v24, v28, v26
	v_div_fmas_f32 v24, v24, v25, v28
	v_div_fixup_f32 v22, v24, v23, v22
	v_mul_f32_e32 v19, v22, v19
	v_lshlrev_b32_e32 v22, 16, v69
	v_mul_f32_e32 v23, 0xbfb8aa3b, v22
	v_exp_f32_e32 v23, v23
	v_cvt_pk_bf16_f32 v18, v18, v19
	s_nop 0
	v_add_f32_e32 v23, 1.0, v23
	v_div_scale_f32 v24, s[0:1], v23, v23, v22
	v_rcp_f32_e32 v25, v24
	s_nop 0
	v_fma_f32 v26, -v24, v25, 1.0
	v_fmac_f32_e32 v25, v26, v25
	v_div_scale_f32 v26, vcc, v22, v23, v22
	v_mul_f32_e32 v28, v26, v25
	v_fma_f32 v30, -v24, v28, v26
	v_fmac_f32_e32 v28, v30, v25
	v_fma_f32 v24, -v24, v28, v26
	v_div_fmas_f32 v24, v24, v25, v28
	v_div_fixup_f32 v22, v24, v23, v22
	v_mul_f32_e32 v20, v22, v20
	v_mul_f32_e32 v22, 0xbfb8aa3b, v21
	v_exp_f32_e32 v22, v22
	s_nop 0
	v_add_f32_e32 v22, 1.0, v22
	v_div_scale_f32 v23, s[0:1], v22, v22, v21
	v_rcp_f32_e32 v24, v23
	s_nop 0
	v_fma_f32 v25, -v23, v24, 1.0
	v_fmac_f32_e32 v24, v25, v24
	v_div_scale_f32 v25, vcc, v21, v22, v21
	v_mul_f32_e32 v26, v25, v24
	v_fma_f32 v28, -v23, v26, v25
	v_fmac_f32_e32 v26, v28, v24
	v_fma_f32 v23, -v23, v26, v25
	v_div_fmas_f32 v23, v23, v24, v26
	v_div_fixup_f32 v21, v23, v22, v21
	v_mul_f32_e32 v0, v21, v0
	v_cvt_pk_bf16_f32 v19, v20, v0
	v_add_f32_e32 v0, 0, v27
	v_add_f32_e32 v0, v0, v29
	v_add_f32_e32 v0, v0, v31
	v_add_f32_e32 v0, v0, v33
	v_add_f32_e32 v0, v0, v35
	v_add_f32_e32 v0, v0, v37
	v_add_f32_e32 v0, v0, v39
	v_add_f32_e32 v0, v0, v41
	v_fmamk_f32 v0, v0, 0x3b800000, v203
	v_mov_b32_e32 v116, v18
	v_mov_b32_e32 v117, v19
	global_store_dwordx4 v[44:45], v[116:119], off
	v_cmp_gt_f32_e32 vcc, s89, v0
	v_mul_f32_e32 v18, 0x4b800000, v0
	s_nop 0
	v_cndmask_b32_e32 v0, v0, v18, vcc
	v_rsq_f32_e32 v0, v0
	s_nop 0
	v_mul_f32_e32 v18, 0x45800000, v0
	v_cndmask_b32_e32 v0, v0, v18, vcc
	v_mul_f32_e32 v10, v10, v0
	v_mul_f32_e32 v10, v14, v10
	v_lshlrev_b32_e32 v14, 16, v64
	v_mul_f32_e32 v20, 0xbfb8aa3b, v14
	v_exp_f32_e32 v20, v20
	v_mul_f32_e32 v11, v11, v0
	v_mul_f32_e32 v11, v15, v11
	v_mul_f32_e32 v12, v12, v0
	v_add_f32_e32 v20, 1.0, v20
	v_div_scale_f32 v21, s[0:1], v20, v20, v14
	v_rcp_f32_e32 v22, v21
	v_mul_f32_e32 v12, v16, v12
	v_mul_f32_e32 v13, v13, v0
	v_mul_f32_e32 v13, v17, v13
	v_fma_f32 v23, -v21, v22, 1.0
	v_fmac_f32_e32 v22, v23, v22
	v_div_scale_f32 v23, vcc, v14, v20, v14
	v_mul_f32_e32 v24, v23, v22
	v_fma_f32 v25, -v21, v24, v23
	v_fmac_f32_e32 v24, v25, v22
	v_fma_f32 v21, -v21, v24, v23
	v_div_fmas_f32 v21, v21, v22, v24
	v_div_fixup_f32 v14, v21, v20, v14
	v_mul_f32_e32 v10, v14, v10
	v_and_b32_e32 v14, 0xffff0000, v64
	v_mul_f32_e32 v15, 0xbfb8aa3b, v14
	v_exp_f32_e32 v15, v15
	v_lshlrev_b64 v[18:19], 12, v[66:67]
	v_mul_f32_e32 v2, v2, v0
	v_lshl_add_u64 v[18:19], v[42:43], 0, v[18:19]
	v_add_f32_e32 v15, 1.0, v15
	v_div_scale_f32 v20, s[0:1], v15, v15, v14
	v_rcp_f32_e32 v21, v20
	v_mul_f32_e32 v2, v6, v2
	v_lshlrev_b32_e32 v6, 16, v62
	v_mul_f32_e32 v3, v3, v0
	v_fma_f32 v22, -v20, v21, 1.0
	v_fmac_f32_e32 v21, v22, v21
	v_div_scale_f32 v22, vcc, v14, v15, v14
	v_mul_f32_e32 v23, v22, v21
	v_fma_f32 v24, -v20, v23, v22
	v_fmac_f32_e32 v23, v24, v21
	v_fma_f32 v20, -v20, v23, v22
	v_div_fmas_f32 v20, v20, v21, v23
	v_div_fixup_f32 v14, v20, v15, v14
	v_mul_f32_e32 v11, v14, v11
	v_lshlrev_b32_e32 v14, 16, v65
	v_mul_f32_e32 v15, 0xbfb8aa3b, v14
	v_exp_f32_e32 v15, v15
	v_cvt_pk_bf16_f32 v10, v10, v11
	v_mul_f32_e32 v3, v7, v3
	v_mul_f32_e32 v4, v4, v0
	v_add_f32_e32 v15, 1.0, v15
	v_div_scale_f32 v16, s[0:1], v15, v15, v14
	v_rcp_f32_e32 v20, v16
	v_mul_f32_e32 v4, v8, v4
	v_mul_f32_e32 v0, v5, v0
	v_and_b32_e32 v5, 0xffff0000, v63
	v_fma_f32 v21, -v16, v20, 1.0
	v_fmac_f32_e32 v20, v21, v20
	v_div_scale_f32 v21, vcc, v14, v15, v14
	v_mul_f32_e32 v22, v21, v20
	v_fma_f32 v23, -v16, v22, v21
	v_fmac_f32_e32 v22, v23, v20
	v_fma_f32 v16, -v16, v22, v21
	v_div_fmas_f32 v16, v16, v20, v22
	v_div_fixup_f32 v14, v16, v15, v14
	v_mul_f32_e32 v12, v14, v12
	v_and_b32_e32 v14, 0xffff0000, v65
	v_mul_f32_e32 v15, 0xbfb8aa3b, v14
	v_exp_f32_e32 v15, v15
	v_mul_f32_e32 v0, v9, v0
	v_add_f32_e32 v15, 1.0, v15
	v_div_scale_f32 v16, s[0:1], v15, v15, v14
	v_rcp_f32_e32 v17, v16
	s_nop 0
	v_fma_f32 v20, -v16, v17, 1.0
	v_fmac_f32_e32 v17, v20, v17
	v_div_scale_f32 v20, vcc, v14, v15, v14
	v_mul_f32_e32 v21, v20, v17
	v_fma_f32 v22, -v16, v21, v20
	v_fmac_f32_e32 v21, v22, v17
	v_fma_f32 v16, -v16, v21, v20
	v_div_fmas_f32 v16, v16, v17, v21
	v_div_fixup_f32 v14, v16, v15, v14
	v_mul_f32_e32 v13, v14, v13
	v_cvt_pk_bf16_f32 v11, v12, v13
	v_mov_b32_e32 v118, v10
	v_mov_b32_e32 v119, v11
	v_mul_f32_e32 v10, 0xbfb8aa3b, v6
	v_exp_f32_e32 v10, v10
	s_nop 0
	v_add_f32_e32 v10, 1.0, v10
	v_div_scale_f32 v11, s[0:1], v10, v10, v6
	v_rcp_f32_e32 v12, v11
	s_nop 0
	v_fma_f32 v13, -v11, v12, 1.0
	v_fmac_f32_e32 v12, v13, v12
	v_div_scale_f32 v13, vcc, v6, v10, v6
	v_mul_f32_e32 v14, v13, v12
	v_fma_f32 v15, -v11, v14, v13
	v_fmac_f32_e32 v14, v15, v12
	v_fma_f32 v11, -v11, v14, v13
	v_div_fmas_f32 v11, v11, v12, v14
	v_div_fixup_f32 v6, v11, v10, v6
	v_mul_f32_e32 v2, v6, v2
	v_and_b32_e32 v6, 0xffff0000, v62
	v_mul_f32_e32 v7, 0xbfb8aa3b, v6
	v_exp_f32_e32 v7, v7
	s_nop 0
	v_add_f32_e32 v7, 1.0, v7
	v_div_scale_f32 v10, s[0:1], v7, v7, v6
	v_rcp_f32_e32 v11, v10
	s_nop 0
	v_fma_f32 v12, -v10, v11, 1.0
	v_fmac_f32_e32 v11, v12, v11
	v_div_scale_f32 v12, vcc, v6, v7, v6
	v_mul_f32_e32 v13, v12, v11
	v_fma_f32 v14, -v10, v13, v12
	v_fmac_f32_e32 v13, v14, v11
	v_fma_f32 v10, -v10, v13, v12
	v_div_fmas_f32 v10, v10, v11, v13
	v_div_fixup_f32 v6, v10, v7, v6
	v_mul_f32_e32 v3, v6, v3
	v_lshlrev_b32_e32 v6, 16, v63
	v_mul_f32_e32 v7, 0xbfb8aa3b, v6
	v_exp_f32_e32 v7, v7
	v_cvt_pk_bf16_f32 v2, v2, v3
	s_nop 0
	v_add_f32_e32 v7, 1.0, v7
	v_div_scale_f32 v8, s[0:1], v7, v7, v6
	v_rcp_f32_e32 v10, v8
	s_nop 0
	v_fma_f32 v11, -v8, v10, 1.0
	v_fmac_f32_e32 v10, v11, v10
	v_div_scale_f32 v11, vcc, v6, v7, v6
	v_mul_f32_e32 v12, v11, v10
	v_fma_f32 v13, -v8, v12, v11
	v_fmac_f32_e32 v12, v13, v10
	v_fma_f32 v8, -v8, v12, v11
	v_div_fmas_f32 v8, v8, v10, v12
	v_div_fixup_f32 v6, v8, v7, v6
	v_mul_f32_e32 v4, v6, v4
	v_mul_f32_e32 v6, 0xbfb8aa3b, v5
	v_exp_f32_e32 v6, v6
	s_nop 0
	v_add_f32_e32 v6, 1.0, v6
	v_div_scale_f32 v7, s[0:1], v6, v6, v5
	v_rcp_f32_e32 v8, v7
	s_mov_b64 s[0:1], 0
	v_fma_f32 v9, -v7, v8, 1.0
	v_fmac_f32_e32 v8, v9, v8
	v_div_scale_f32 v9, vcc, v5, v6, v5
	v_mul_f32_e32 v10, v9, v8
	v_fma_f32 v11, -v7, v10, v9
	v_fmac_f32_e32 v10, v11, v8
	v_fma_f32 v7, -v7, v10, v9
	v_div_fmas_f32 v7, v7, v8, v10
	v_div_fixup_f32 v5, v7, v6, v5
	v_mul_f32_e32 v0, v5, v0
	v_cvt_pk_bf16_f32 v3, v4, v0
	v_mov_b32_e32 v116, v2
	v_mov_b32_e32 v117, v3
	global_store_dwordx4 v[18:19], v[116:119], off
	s_barrier
